# indexer phase: mirror of the static priority raise (waves 0-3 at s_setprio 1), reset at the phase's closing barrier
# speedup vs baseline: 1.0023x; 1.0023x over previous
; __device__ __forceinline__ int fresh_tid() { int t = threadIdx.x; asm volatile("" : "+v"(t)); return t; }
; #define LAS __attribute__((address_space(3)))
; __device__ __forceinline__ void indexer_phase(const bf16_t* PJ, float* rk, unsigned short* SEL, LAS unsigned char* lds) {
;     const int tid = fresh_tid(), lane = tid & 63, r32 = lane & 31, hi = lane >> 5;
;     const int wid = __builtin_amdgcn_readfirstlane(tid >> 6);
;     { const int gw = blockIdx.x * NWAVE + wid, NGW = gridDim.x * NWAVE;
;       for (int t4 = gw; t4 < TOK / 4; t4 += NGW) { const int tok = 4 * t4 + (lane >> 4);
;           const u32x4 w = *(const u32x4*)(PJ + (size_t)tok * PROJ_LD + PJ_LAT + 8 * (lane & 15));
;           float ss = bflo(w.x) * bflo(w.x) + bfhi(w.x) * bfhi(w.x) + bflo(w.y) * bflo(w.y) + bfhi(w.y) * bfhi(w.y) + bflo(w.z) * bflo(w.z) + bfhi(w.z) * bfhi(w.z) + bflo(w.w) * bflo(w.w) + bfhi(w.w) * bfhi(w.w);
;           ss += __shfl_xor(ss, 1); ss += __shfl_xor(ss, 2); ss += __shfl_xor(ss, 4); ss += __shfl_xor(ss, 8);
;           if ((lane & 15) == 0) rk[tok] = rsqrtf(ss * (1.f / 128.f) + RMS_EPS); } }
;     constexpr int AUX0 = 131072, AUXW = 3072;
;     LAS unsigned* hist = (LAS unsigned*)(lds + AUX0 + wid * AUXW);
;     LAS unsigned short* listA = (LAS unsigned short*)(lds + AUX0 + wid * AUXW + 2080);
;     LAS float* pmm = (LAS float*)(lds + AUX0 + NWAVE * AUXW);
.LBB0_861:
	s_cmpk_gt_i32 s76, 0xfff
	s_cbranch_scc1 .LBB0_1030
	v_writelane_b32 v255, s60, 15
	s_mul_i32 s0, s33, 0xc00
	s_add_i32 s94, s0, 0
	v_writelane_b32 v255, s61, 16
	v_writelane_b32 v255, s59, 17
	s_add_i32 s94, s94, 0x20000
	v_writelane_b32 v255, s82, 18
	s_add_u32 s4, s10, 0x1e400000
	s_addc_u32 s5, s11, 0
	v_writelane_b32 v255, s83, 19
	s_lshl_b32 s0, s33, 5
	s_mul_i32 s2, s33, 0x2c000
	v_writelane_b32 v255, s0, 20
	s_mul_hi_i32 s3, s0, 0x1600
	v_lshrrev_b32_e32 v1, 5, v108
	v_writelane_b32 v255, s2, 21
	v_lshrrev_b32_e32 v2, 1, v6
	v_bfe_u32 v3, v6, 4, 1
	v_lshlrev_b32_e32 v116, 1, v1
	v_writelane_b32 v255, s3, 22
	s_lshl_b32 s0, s33, 3
	v_and_or_b32 v112, v2, 2, v3
	v_writelane_b32 v255, s0, 23
	v_or_b32_e32 v3, s0, v116
	s_lshl_b32 s0, s33, 14
	s_add_i32 s96, s0, 0
	v_mov_b32_e32 v4, 0x200
	v_lshl_add_u32 v119, v108, 5, s94
	s_movk_i32 s0, 0xffe4
	v_and_b32_e32 v0, 3, v6
	v_and_or_b32 v113, v6, 7, v4
	v_mad_i32_i24 v158, v108, s0, v119
	v_or_b32_e32 v4, 0x200, v108
	s_movk_i32 s0, 0x208
	v_and_or_b32 v0, v2, 4, v0
	v_cmp_gt_u32_e64 s[10:11], s0, v4
	s_lshl_b32 s0, s33, 7
	v_and_b32_e32 v110, 31, v6
	v_lshlrev_b32_e32 v0, 6, v0
	v_lshlrev_b32_e32 v2, 3, v1
	v_lshlrev_b32_e32 v118, 2, v108
	v_lshl_add_u32 v1, v1, 15, s0
	v_lshlrev_b32_e32 v117, 3, v108
	v_add_u32_e32 v159, v158, v118
	v_lshlrev_b32_e32 v160, 3, v3
	v_sub_u32_e32 v3, 0, v118
	v_lshl_or_b32 v1, v110, 2, v1
	v_lshlrev_b32_e32 v114, 1, v0
	v_mbcnt_hi_u32_b32 v180, -1, v195
	v_mov_b32_e32 v0, 0x80
	v_mov_b32_e32 v115, 0
	s_movk_i32 s7, 0x1600
	v_cmp_eq_u32_e64 s[8:9], 0, v110
	v_lshl_add_u32 v111, v108, 4, s96
	v_or_b32_e32 v121, 0x100, v108
	v_or_b32_e32 v120, 1, v116
	v_cmp_eq_u32_e64 s[12:13], 63, v108
	v_cmp_gt_u32_e64 s[14:15], 62, v108
	v_cmp_gt_u32_e64 s[16:17], 60, v108
	v_cmp_gt_u32_e64 s[18:19], 56, v108
	v_cmp_gt_u32_e64 s[20:21], 48, v108
	v_cmp_gt_u32_e64 s[22:23], 32, v108
	v_or_b32_e32 v161, 7, v117
	v_or_b32_e32 v162, 6, v117
	v_or_b32_e32 v163, 5, v117
	v_or_b32_e32 v164, 4, v117
	v_or_b32_e32 v165, 3, v117
	v_or_b32_e32 v166, 2, v117
	v_or_b32_e32 v167, 1, v117
	v_or_b32_e32 v168, 64, v108
	v_or_b32_e32 v169, 0x80, v108
	v_or_b32_e32 v170, 0xc0, v108
	v_mov_b32_e32 v109, v108
	v_add_u32_e32 v171, 0, v1
	v_or_b32_e32 v172, 0x100, v118
	v_add_u32_e32 v173, s96, v118
	v_lshlrev_b32_e32 v122, 1, v2
	s_movk_i32 s44, 0x1000
	s_mov_b32 s58, 0x3eb504f3
	s_mov_b32 s45, 0x43ff8000
	v_mov_b32_e32 v174, 1
	v_lshlrev_b32_e32 v175, 1, v118
	v_lshlrev_b32_e32 v176, 1, v108
	v_mov_b32_e32 v177, 0x1600
	v_mov_b32_e32 v178, 0xff800000
	v_mov_b32_e32 v179, 0x7f800000
	v_lshl_or_b32 v181, v180, 2, v0
	v_add_u32_e32 v182, v159, v3
	s_mov_b32 s2, s76
	v_lshrrev_b32_e32 v222, 2, v108
	v_and_b32_e32 v223, 31, v108
	v_sub_u32_e32 v218, v222, v223
	v_mul_i32_i24_e32 v218, 0x1600, v218
	v_and_b32_e32 v224, 3, v108
	v_lshrrev_b32_e32 v225, 5, v108
	v_sub_u32_e32 v219, v224, v225
	v_lshl_add_u32 v218, v219, 4, v218
	v_ashrrev_i32_e32 v219, 31, v218
	v_bfe_u32 v226, v108, 4, 2
	v_xor_b32_e32 v226, v224, v226
	v_lshlrev_b32_e32 v226, 4, v226
	v_lshl_add_u32 v222, v222, 6, v226
	v_add_u32_e32 v222, s94, v222
	v_bfe_u32 v226, v108, 2, 2
	v_xor_b32_e32 v226, v225, v226
	v_lshlrev_b32_e32 v226, 4, v226
	v_lshl_add_u32 v223, v223, 6, v226
	v_add_u32_e32 v223, s94, v223
	v_xor_b32_e32 v224, 32, v223
	s_cmp_lt_u32 s33, 4
	s_cbranch_scc0 .Lidx_noprio
	s_setprio 1
